# windowed-attention epilogue: v_permlane32_swap pairs neighbouring column groups so each lane stores 16 contiguous bytes (8 global_store_dwordx4 per wave instead of 16 dwordx2)
# speedup vs baseline: 1.0034x; 1.0034x over previous
.LBB0_373:
	s_ashr_i32 s5, s4, 31
	s_lshl_b64 s[4:5], s[4:5], 2
	s_add_u32 s4, s12, s4
	s_addc_u32 s5, s13, s5
	global_load_dword v0, v1, s[4:5]
	s_mov_b32 s4, 0x3fb8aa3b
	s_waitcnt vmcnt(0)
	v_fma_f32 v0, v0, s4, -v223
	s_add_u32 s4, s18, s6
	v_exp_f32_e32 v72, v0
	s_addc_u32 s5, s19, s7
	v_lshlrev_b32_e32 v0, 2, v224
	v_lshl_add_u64 v[66:67], s[4:5], 0, v[0:1]
	ds_bpermute_b32 v0, v221, v228
	s_add_i32 s17, s17, s54
	s_add_i32 s16, s16, s54
	s_cmpk_gt_i32 s17, 0xff
	s_waitcnt lgkmcnt(0)
	v_add_f32_e32 v0, v228, v0
	v_add_f32_e32 v0, v72, v0
	v_div_scale_f32 v68, s[4:5], v0, v0, 1.0
	v_rcp_f32_e32 v69, v68
	s_nop 0
	v_fma_f32 v70, -v68, v69, 1.0
	v_fmac_f32_e32 v69, v70, v69
	v_div_scale_f32 v70, vcc, 1.0, v0, 1.0
	v_mul_f32_e32 v71, v70, v69
	v_fma_f32 v73, -v68, v71, v70
	v_fmac_f32_e32 v71, v73, v69
	v_fma_f32 v68, -v68, v71, v70
	v_div_fmas_f32 v68, v68, v69, v71
	v_div_fixup_f32 v0, v68, v0, 1.0
	v_lshlrev_b64 v[68:69], 11, v[206:207]
	v_lshl_add_u64 v[70:71], v[66:67], 0, v[68:69]
	v_mul_f32_e32 v50, v50, v0
	v_mul_f32_e32 v51, v51, v0
	v_cvt_pk_bf16_f32 v50, v50, v51
	v_mul_f32_e32 v51, v52, v0
	v_mul_f32_e32 v52, v53, v0
	v_cvt_pk_bf16_f32 v51, v51, v52
	v_mul_f32_e32 v52, v54, v0
	v_mul_f32_e32 v53, v55, v0
	v_cvt_pk_bf16_f32 v52, v52, v53
	v_mul_f32_e32 v53, v56, v0
	v_mul_f32_e32 v54, v57, v0
	v_cvt_pk_bf16_f32 v53, v53, v54
	s_nop 1
	v_permlane32_swap_b32 v50, v52
	v_permlane32_swap_b32 v51, v53
	global_store_dwordx4 v[70:71], v[50:53], off
	v_mul_f32_e32 v58, v58, v0
	v_mul_f32_e32 v59, v59, v0
	v_cvt_pk_bf16_f32 v58, v58, v59
	v_mul_f32_e32 v59, v60, v0
	v_mul_f32_e32 v60, v61, v0
	v_cvt_pk_bf16_f32 v59, v59, v60
	v_mul_f32_e32 v60, v62, v0
	v_mul_f32_e32 v61, v63, v0
	v_cvt_pk_bf16_f32 v60, v60, v61
	v_mul_f32_e32 v61, v64, v0
	v_mul_f32_e32 v62, v65, v0
	v_cvt_pk_bf16_f32 v61, v61, v62
	s_nop 1
	v_permlane32_swap_b32 v58, v60
	v_permlane32_swap_b32 v59, v61
	global_store_dwordx4 v[70:71], v[58:61], off offset:32
	v_mul_f32_e32 v34, v34, v0
	v_mul_f32_e32 v35, v35, v0
	v_cvt_pk_bf16_f32 v34, v34, v35
	v_mul_f32_e32 v35, v36, v0
	v_mul_f32_e32 v36, v37, v0
	v_cvt_pk_bf16_f32 v35, v35, v36
	v_mul_f32_e32 v36, v38, v0
	v_mul_f32_e32 v37, v39, v0
	v_cvt_pk_bf16_f32 v36, v36, v37
	v_mul_f32_e32 v37, v40, v0
	v_mul_f32_e32 v38, v41, v0
	v_cvt_pk_bf16_f32 v37, v37, v38
	s_nop 1
	v_permlane32_swap_b32 v34, v36
	v_permlane32_swap_b32 v35, v37
	global_store_dwordx4 v[70:71], v[34:37], off offset:64
	v_mul_f32_e32 v42, v42, v0
	v_mul_f32_e32 v43, v43, v0
	v_cvt_pk_bf16_f32 v42, v42, v43
	v_mul_f32_e32 v43, v44, v0
	v_mul_f32_e32 v44, v45, v0
	v_cvt_pk_bf16_f32 v43, v43, v44
	v_mul_f32_e32 v44, v46, v0
	v_mul_f32_e32 v45, v47, v0
	v_cvt_pk_bf16_f32 v44, v44, v45
	v_mul_f32_e32 v45, v48, v0
	v_mul_f32_e32 v46, v49, v0
	v_cvt_pk_bf16_f32 v45, v45, v46
	ds_bpermute_b32 v0, v221, v209
	s_nop 1
	v_permlane32_swap_b32 v42, v44
	v_permlane32_swap_b32 v43, v45
	global_store_dwordx4 v[70:71], v[42:45], off offset:96
	v_or_b32_e32 v68, 0x10000, v68
	s_waitcnt lgkmcnt(0)
	v_add_f32_e32 v0, v209, v0
	v_add_f32_e32 v0, v72, v0
	v_div_scale_f32 v34, s[4:5], v0, v0, 1.0
	v_rcp_f32_e32 v35, v34
	s_nop 0
	v_fma_f32 v36, -v34, v35, 1.0
	v_fmac_f32_e32 v35, v36, v35
	v_div_scale_f32 v36, vcc, 1.0, v0, 1.0
	v_mul_f32_e32 v37, v36, v35
	v_fma_f32 v38, -v34, v37, v36
	v_fmac_f32_e32 v37, v38, v35
	v_fma_f32 v34, -v34, v37, v36
	v_div_fmas_f32 v34, v34, v35, v37
	v_div_fixup_f32 v0, v34, v0, 1.0
	v_lshl_add_u64 v[34:35], v[66:67], 0, v[68:69]
	v_mul_f32_e32 v18, v18, v0
	v_mul_f32_e32 v19, v19, v0
	v_cvt_pk_bf16_f32 v18, v18, v19
	v_mul_f32_e32 v19, v20, v0
	v_mul_f32_e32 v20, v21, v0
	v_cvt_pk_bf16_f32 v19, v19, v20
	v_mul_f32_e32 v20, v22, v0
	v_mul_f32_e32 v21, v23, v0
	v_cvt_pk_bf16_f32 v20, v20, v21
	v_mul_f32_e32 v21, v24, v0
	v_mul_f32_e32 v22, v25, v0
	v_cvt_pk_bf16_f32 v21, v21, v22
	s_nop 1
	v_permlane32_swap_b32 v18, v20
	v_permlane32_swap_b32 v19, v21
	global_store_dwordx4 v[34:35], v[18:21], off
	v_mul_f32_e32 v26, v26, v0
	v_mul_f32_e32 v27, v27, v0
	v_cvt_pk_bf16_f32 v26, v26, v27
	v_mul_f32_e32 v27, v28, v0
	v_mul_f32_e32 v28, v29, v0
	v_cvt_pk_bf16_f32 v27, v27, v28
	v_mul_f32_e32 v28, v30, v0
	v_mul_f32_e32 v29, v31, v0
	v_cvt_pk_bf16_f32 v28, v28, v29
	v_mul_f32_e32 v29, v32, v0
	v_mul_f32_e32 v30, v33, v0
	v_cvt_pk_bf16_f32 v29, v29, v30
	s_nop 1
	v_permlane32_swap_b32 v26, v28
	v_permlane32_swap_b32 v27, v29
	global_store_dwordx4 v[34:35], v[26:29], off offset:32
	v_mul_f32_e32 v2, v2, v0
	v_mul_f32_e32 v3, v3, v0
	v_cvt_pk_bf16_f32 v2, v2, v3
	v_mul_f32_e32 v3, v4, v0
	v_mul_f32_e32 v4, v5, v0
	v_cvt_pk_bf16_f32 v3, v3, v4
	v_mul_f32_e32 v4, v6, v0
	v_mul_f32_e32 v5, v7, v0
	v_cvt_pk_bf16_f32 v4, v4, v5
	v_mul_f32_e32 v5, v8, v0
	v_mul_f32_e32 v6, v9, v0
	v_cvt_pk_bf16_f32 v5, v5, v6
	s_nop 1
	v_permlane32_swap_b32 v2, v4
	v_permlane32_swap_b32 v3, v5
	global_store_dwordx4 v[34:35], v[2:5], off offset:64
	v_mul_f32_e32 v10, v10, v0
	v_mul_f32_e32 v11, v11, v0
	v_cvt_pk_bf16_f32 v10, v10, v11
	v_mul_f32_e32 v11, v12, v0
	v_mul_f32_e32 v12, v13, v0
	v_cvt_pk_bf16_f32 v11, v11, v12
	v_mul_f32_e32 v12, v14, v0
	v_mul_f32_e32 v13, v15, v0
	v_cvt_pk_bf16_f32 v12, v12, v13
	v_mul_f32_e32 v13, v16, v0
	v_mul_f32_e32 v14, v17, v0
	v_cvt_pk_bf16_f32 v13, v13, v14
	s_nop 1
	v_permlane32_swap_b32 v10, v12
	v_permlane32_swap_b32 v11, v13
	global_store_dwordx4 v[34:35], v[10:13], off offset:96
	s_nop 1
	s_cbranch_scc1 .LBB0_385
